# phase-0 adaLN GEMV: 32 weight loads in flight per lane (4 round trips per job instead of 16), plain v_fmac accumulation (bit-identical)
# speedup vs baseline: 1.0139x; 1.0015x over previous
.LBB0_742:
	v_lshl_add_u64 v[76:77], v[4:5], 0, s[10:11]
	s_mov_b32 s98, 0x6000
	s_mov_b32 s99, 0
	global_load_dword v148, v[76:77], off
	v_lshl_add_u64 v[76:77], v[76:77], 0, s[98:99]
	global_load_dword v149, v[76:77], off
	v_lshl_add_u64 v[76:77], v[76:77], 0, s[98:99]
	global_load_dword v150, v[76:77], off
	v_lshl_add_u64 v[76:77], v[76:77], 0, s[98:99]
	global_load_dword v151, v[76:77], off
	v_lshl_add_u64 v[76:77], v[76:77], 0, s[98:99]
	global_load_dword v152, v[76:77], off
	v_lshl_add_u64 v[76:77], v[76:77], 0, s[98:99]
	global_load_dword v153, v[76:77], off
	v_lshl_add_u64 v[76:77], v[76:77], 0, s[98:99]
	global_load_dword v154, v[76:77], off
	v_lshl_add_u64 v[76:77], v[76:77], 0, s[98:99]
	global_load_dword v155, v[76:77], off
	v_lshl_add_u64 v[76:77], v[76:77], 0, s[98:99]
	global_load_dword v156, v[76:77], off
	v_lshl_add_u64 v[76:77], v[76:77], 0, s[98:99]
	global_load_dword v157, v[76:77], off
	v_lshl_add_u64 v[76:77], v[76:77], 0, s[98:99]
	global_load_dword v158, v[76:77], off
	v_lshl_add_u64 v[76:77], v[76:77], 0, s[98:99]
	global_load_dword v159, v[76:77], off
	v_lshl_add_u64 v[76:77], v[76:77], 0, s[98:99]
	global_load_dword v160, v[76:77], off
	v_lshl_add_u64 v[76:77], v[76:77], 0, s[98:99]
	global_load_dword v161, v[76:77], off
	v_lshl_add_u64 v[76:77], v[76:77], 0, s[98:99]
	global_load_dword v162, v[76:77], off
	v_lshl_add_u64 v[76:77], v[76:77], 0, s[98:99]
	global_load_dword v163, v[76:77], off
	v_lshl_add_u64 v[76:77], v[76:77], 0, s[98:99]
	global_load_dword v164, v[76:77], off
	v_lshl_add_u64 v[76:77], v[76:77], 0, s[98:99]
	global_load_dword v165, v[76:77], off
	v_lshl_add_u64 v[76:77], v[76:77], 0, s[98:99]
	global_load_dword v166, v[76:77], off
	v_lshl_add_u64 v[76:77], v[76:77], 0, s[98:99]
	global_load_dword v167, v[76:77], off
	v_lshl_add_u64 v[76:77], v[76:77], 0, s[98:99]
	global_load_dword v168, v[76:77], off
	v_lshl_add_u64 v[76:77], v[76:77], 0, s[98:99]
	global_load_dword v169, v[76:77], off
	v_lshl_add_u64 v[76:77], v[76:77], 0, s[98:99]
	global_load_dword v170, v[76:77], off
	v_lshl_add_u64 v[76:77], v[76:77], 0, s[98:99]
	global_load_dword v171, v[76:77], off
	v_lshl_add_u64 v[76:77], v[76:77], 0, s[98:99]
	global_load_dword v172, v[76:77], off
	v_lshl_add_u64 v[76:77], v[76:77], 0, s[98:99]
	global_load_dword v173, v[76:77], off
	v_lshl_add_u64 v[76:77], v[76:77], 0, s[98:99]
	global_load_dword v174, v[76:77], off
	v_lshl_add_u64 v[76:77], v[76:77], 0, s[98:99]
	global_load_dword v175, v[76:77], off
	v_lshl_add_u64 v[76:77], v[76:77], 0, s[98:99]
	global_load_dword v176, v[76:77], off
	v_lshl_add_u64 v[76:77], v[76:77], 0, s[98:99]
	global_load_dword v177, v[76:77], off
	v_lshl_add_u64 v[76:77], v[76:77], 0, s[98:99]
	global_load_dword v178, v[76:77], off
	v_lshl_add_u64 v[76:77], v[76:77], 0, s[98:99]
	global_load_dword v179, v[76:77], off
	v_mov_b32_e32 v32, s9
	ds_read_b128 v[12:15], v32
	ds_read_b128 v[16:19], v32 offset:16
	ds_read_b128 v[20:23], v32 offset:4096
	ds_read_b128 v[24:27], v32 offset:4112
	ds_read_b128 v[28:31], v32 offset:8192
	ds_read_b128 v[78:81], v32 offset:8208
	s_waitcnt vmcnt(24) lgkmcnt(0)
	v_fmac_f32_e32 v6, v148, v12
	v_fmac_f32_e32 v7, v148, v20
	v_fmac_f32_e32 v11, v148, v28
	v_fmac_f32_e32 v6, v149, v13
	v_fmac_f32_e32 v7, v149, v21
	v_fmac_f32_e32 v11, v149, v29
	v_fmac_f32_e32 v6, v150, v14
	v_fmac_f32_e32 v7, v150, v22
	v_fmac_f32_e32 v11, v150, v30
	v_fmac_f32_e32 v6, v151, v15
	v_fmac_f32_e32 v7, v151, v23
	v_fmac_f32_e32 v11, v151, v31
	v_fmac_f32_e32 v6, v152, v16
	v_fmac_f32_e32 v7, v152, v24
	v_fmac_f32_e32 v11, v152, v78
	v_fmac_f32_e32 v6, v153, v17
	v_fmac_f32_e32 v7, v153, v25
	v_fmac_f32_e32 v11, v153, v79
	v_fmac_f32_e32 v6, v154, v18
	v_fmac_f32_e32 v7, v154, v26
	v_fmac_f32_e32 v11, v154, v80
	v_fmac_f32_e32 v6, v155, v19
	v_fmac_f32_e32 v7, v155, v27
	v_fmac_f32_e32 v11, v155, v81
	ds_read_b128 v[12:15], v32 offset:32
	ds_read_b128 v[16:19], v32 offset:48
	ds_read_b128 v[20:23], v32 offset:4128
	ds_read_b128 v[24:27], v32 offset:4144
	ds_read_b128 v[28:31], v32 offset:8224
	ds_read_b128 v[78:81], v32 offset:8240
	s_waitcnt vmcnt(16) lgkmcnt(0)
	v_fmac_f32_e32 v6, v156, v12
	v_fmac_f32_e32 v7, v156, v20
	v_fmac_f32_e32 v11, v156, v28
	v_fmac_f32_e32 v6, v157, v13
	v_fmac_f32_e32 v7, v157, v21
	v_fmac_f32_e32 v11, v157, v29
	v_fmac_f32_e32 v6, v158, v14
	v_fmac_f32_e32 v7, v158, v22
	v_fmac_f32_e32 v11, v158, v30
	v_fmac_f32_e32 v6, v159, v15
	v_fmac_f32_e32 v7, v159, v23
	v_fmac_f32_e32 v11, v159, v31
	v_fmac_f32_e32 v6, v160, v16
	v_fmac_f32_e32 v7, v160, v24
	v_fmac_f32_e32 v11, v160, v78
	v_fmac_f32_e32 v6, v161, v17
	v_fmac_f32_e32 v7, v161, v25
	v_fmac_f32_e32 v11, v161, v79
	v_fmac_f32_e32 v6, v162, v18
	v_fmac_f32_e32 v7, v162, v26
	v_fmac_f32_e32 v11, v162, v80
	v_fmac_f32_e32 v6, v163, v19
	v_fmac_f32_e32 v7, v163, v27
	v_fmac_f32_e32 v11, v163, v81
	ds_read_b128 v[12:15], v32 offset:64
	ds_read_b128 v[16:19], v32 offset:80
	ds_read_b128 v[20:23], v32 offset:4160
	ds_read_b128 v[24:27], v32 offset:4176
	ds_read_b128 v[28:31], v32 offset:8256
	ds_read_b128 v[78:81], v32 offset:8272
	s_waitcnt vmcnt(8) lgkmcnt(0)
	v_fmac_f32_e32 v6, v164, v12
	v_fmac_f32_e32 v7, v164, v20
	v_fmac_f32_e32 v11, v164, v28
	v_fmac_f32_e32 v6, v165, v13
	v_fmac_f32_e32 v7, v165, v21
	v_fmac_f32_e32 v11, v165, v29
	v_fmac_f32_e32 v6, v166, v14
	v_fmac_f32_e32 v7, v166, v22
	v_fmac_f32_e32 v11, v166, v30
	v_fmac_f32_e32 v6, v167, v15
	v_fmac_f32_e32 v7, v167, v23
	v_fmac_f32_e32 v11, v167, v31
	v_fmac_f32_e32 v6, v168, v16
	v_fmac_f32_e32 v7, v168, v24
	v_fmac_f32_e32 v11, v168, v78
	v_fmac_f32_e32 v6, v169, v17
	v_fmac_f32_e32 v7, v169, v25
	v_fmac_f32_e32 v11, v169, v79
	v_fmac_f32_e32 v6, v170, v18
	v_fmac_f32_e32 v7, v170, v26
	v_fmac_f32_e32 v11, v170, v80
	v_fmac_f32_e32 v6, v171, v19
	v_fmac_f32_e32 v7, v171, v27
	v_fmac_f32_e32 v11, v171, v81
	ds_read_b128 v[12:15], v32 offset:96
	ds_read_b128 v[16:19], v32 offset:112
	ds_read_b128 v[20:23], v32 offset:4192
	ds_read_b128 v[24:27], v32 offset:4208
	ds_read_b128 v[28:31], v32 offset:8288
	ds_read_b128 v[78:81], v32 offset:8304
	s_waitcnt vmcnt(0) lgkmcnt(0)
	v_fmac_f32_e32 v6, v172, v12
	v_fmac_f32_e32 v7, v172, v20
	v_fmac_f32_e32 v11, v172, v28
	v_fmac_f32_e32 v6, v173, v13
	v_fmac_f32_e32 v7, v173, v21
	v_fmac_f32_e32 v11, v173, v29
	v_fmac_f32_e32 v6, v174, v14
	v_fmac_f32_e32 v7, v174, v22
	v_fmac_f32_e32 v11, v174, v30
	v_fmac_f32_e32 v6, v175, v15
	v_fmac_f32_e32 v7, v175, v23
	v_fmac_f32_e32 v11, v175, v31
	v_fmac_f32_e32 v6, v176, v16
	v_fmac_f32_e32 v7, v176, v24
	v_fmac_f32_e32 v11, v176, v78
	v_fmac_f32_e32 v6, v177, v17
	v_fmac_f32_e32 v7, v177, v25
	v_fmac_f32_e32 v11, v177, v79
	v_fmac_f32_e32 v6, v178, v18
	v_fmac_f32_e32 v7, v178, v26
	v_fmac_f32_e32 v11, v178, v80
	v_fmac_f32_e32 v6, v179, v19
	v_fmac_f32_e32 v7, v179, v27
	v_fmac_f32_e32 v11, v179, v81
	s_add_u32 s10, s10, 0xc0000
	s_addc_u32 s11, s11, 0
	s_addk_i32 s9, 0x80
	s_cmp_eq_u32 s10, 0x300000
	s_cbranch_scc0 .LBB0_742
	s_andn2_b64 vcc, exec, s[0:1]
	ds_write2st64_b32 v8, v6, v7 offset0:48 offset1:49
	ds_write_b32 v8, v11 offset:12800
	s_waitcnt lgkmcnt(0)
	s_barrier
	s_cbranch_vccnz .LBB0_740
	s_mul_i32 s9, s12, 0x1800
	s_add_i32 s9, s9, s8
	v_or_b32_e32 v4, s9, v204
	v_readlane_b32 s80, v255, 0
	v_ashrrev_i32_e32 v5, 31, v4
	v_readlane_b32 s84, v255, 4
	v_readlane_b32 s85, v255, 5
	s_mul_i32 s9, s12, 3
	s_mul_hi_i32 s8, s12, 3
	v_lshl_add_u64 v[4:5], v[4:5], 2, s[84:85]
	global_load_dword v11, v[4:5], off
	ds_read2st64_b32 v[4:5], v0 offset0:48 offset1:51
	ds_read2st64_b32 v[6:7], v0 offset0:54 offset1:57
	ds_read2st64_b32 v[12:13], v0 offset0:60 offset1:63
	ds_read2st64_b32 v[14:15], v0 offset0:66 offset1:69
	s_add_u32 s9, s9, s27
	s_waitcnt lgkmcnt(3)
	v_add_f32_e32 v4, 0, v4
	v_add_f32_e32 v4, v4, v5
	s_addc_u32 s8, s8, s2
	s_waitcnt lgkmcnt(2)
	v_add_f32_e32 v4, v4, v6
	s_mul_hi_u32 s10, s9, 0x6000
	s_mulk_i32 s8, 0x6000
	v_add_f32_e32 v4, v4, v7
	s_mulk_i32 s9, 0x6000
	s_add_i32 s10, s10, s8
	s_waitcnt lgkmcnt(1)
	v_add_f32_e32 v4, v4, v12
	s_add_u32 s8, s42, s9
	v_add_f32_e32 v4, v4, v13
	s_addc_u32 s9, s71, s10
	s_waitcnt lgkmcnt(0)
	v_add_f32_e32 v4, v4, v14
	s_add_u32 s6, s8, s6
	v_add_f32_e32 v4, v4, v15
	s_addc_u32 s7, s9, s7
	v_readlane_b32 s81, v255, 1
	v_readlane_b32 s82, v255, 2
	v_readlane_b32 s83, v255, 3
	v_readlane_b32 s86, v255, 6
	v_readlane_b32 s87, v255, 7
	v_readlane_b32 s88, v255, 8
	v_readlane_b32 s89, v255, 9
	v_readlane_b32 s90, v255, 10
	v_readlane_b32 s91, v255, 11
	v_readlane_b32 s92, v255, 12
	v_readlane_b32 s93, v255, 13
	v_readlane_b32 s94, v255, 14
	v_readlane_b32 s95, v255, 15
	s_waitcnt vmcnt(0)
	v_add_f32_e32 v4, v4, v11
	global_store_dword v9, v4, s[6:7]
	s_branch .LBB0_740
